# v82 + P1 x-pass jobs dealt 5 per block to blocks with two shift-table jobs and 7-8 to the others
# baseline (speedup 1.0000x reference)
.LBB0_168:
	s_waitcnt lgkmcnt(0)
	s_cmpk_lg_u32 s38, 0x100
	s_cbranch_scc1 .Lp1_orig
	s_cmpk_ge_i32 s61, 0x188
	s_cbranch_scc1 .Lp1_xp
	s_add_i32 s61, s61, 0x100
	s_cmpk_lt_i32 s61, 0x188
	s_cbranch_scc1 .LBB0_169
	s_add_i32 s6, s92, 0x188
	s_add_i32 s7, s92, 0x3a8
	s_cmpk_ge_u32 s92, 0x88
	s_cselect_b32 s61, s7, s6
	s_branch .LBB0_169
.Lp1_xp:
	s_cmpk_ge_u32 s92, 0x88
	s_cbranch_scc1 .Lp1_xpB
	s_add_i32 s61, s61, 0x88
	s_cmpk_lt_i32 s61, 0x430
	s_cbranch_scc1 .LBB0_169
	s_branch .LBB0_214
.Lp1_xpB:
	s_cmpk_ge_i32 s61, 0x778
	s_cbranch_scc1 .LBB0_214
	s_add_i32 s61, s61, 0x78
	s_cmpk_lt_i32 s61, 0x778
	s_cbranch_scc1 .LBB0_169
	s_cmpk_ge_u32 s92, 0x98
	s_cbranch_scc1 .LBB0_214
	s_add_i32 s61, s92, 0x6f0
	s_branch .LBB0_169
.Lp1_orig:
	s_add_i32 s61, s61, s38
	s_cmpk_gt_i32 s61, 0x787
	s_cbranch_scc1 .LBB0_214
